# layer-1 in-proj: skip the 8 N-tiles per ctx M-tile that nothing reads (last layer emits no ctx output) and re-balance M-tiles over XCDs so max tiles per CU is 8
# speedup vs baseline: 1.2872x; 1.0112x over previous
; DI int tidx() { int t = threadIdx.x; asm volatile("" : "+v"(t)); return t; }
; template <int EPI>
; DI bool tile_coords(int j, int mpx, int& m0, int& n0) {
;   const int x = blockIdx.x & 7, s = blockIdx.x >> 3, ns = gridDim.x >> 3;
;   const int q = s + ns * j;
;   if constexpr (EPI == 0) {
;     if (q >= mpx * 15) return false;
;     const int panel = q / 90, i = q % 90;
;     const int nt = i / 6, mi = i % 6;
;     m0 = (x * mpx + panel * 6 + mi) * 256;
;     n0 = nt * 256;
; template <int EPI>
; DI void gemm_phase(const P& p, int l, const u16* __restrict__ A, const u16* __restrict__ Bt, int mpx, char* lds) {
;   const int tid = tidx();
;   int t = 0;
;   int m0, n0;
;   if (!tile_coords<EPI>(t, mpx, m0, n0)) return;
;   const unsigned voffb = (unsigned)(((tid >> 3) * 1024 + (tid & 7) * 8) * 2);
;   const u16* Ag = A + (size_t)m0 * 1024;
;   const u16* Bg = Bt + (size_t)n0 * 1024;
;   uint4 ra0, ra1, ra2, ra3, rb0, rb1, rb2, rb3;
;     ...
;   GLOAD(Ag, Bg, 0)
;   u16* As0 = (u16*)lds;
;   u16* Bs0 = As0 + 256 * 64;
;   u16* As1 = Bs0 + 256 * 64;
;   u16* Bs1 = As1 + 256 * 64;
;   const int lw = (tid >> 3) * 64 + (((tid & 7) ^ ((tid >> 3) & 7)) * 8);
;   GSTORE(As0, Bs0)
.LBB0_74:
	s_andn2_b64 vcc, exec, s[0:1]
	s_cbranch_vccnz .LBB0_941
	s_cmp_lg_u32 s24, 1
	s_mov_b64 s[0:1], -1
	s_cbranch_scc0 .LBB0_812
	v_readlane_b32 s0, v254, 9
	v_readlane_b32 s1, v254, 10
	v_mov_b32_e32 v0, v195
	s_andn2_b64 vcc, exec, s[0:1]
	s_cbranch_vccnz .LBB0_811
	s_cmp_lg_u32 s50, 1
	s_cbranch_scc1 .Ltile_fix_done
	v_readlane_b32 s42, v254, 11
	s_lshl_b32 s43, s42, 20
	s_lshl_b32 s42, s42, 9
	v_readlane_b32 s40, v254, 58
	s_sub_i32 s40, s40, s42
	s_nop 1
	v_writelane_b32 v254, s40, 58
	v_readlane_b32 s40, v254, 61
	v_readlane_b32 s41, v254, 62
	s_sub_u32 s40, s40, s43
	s_subb_u32 s41, s41, 0
	s_nop 1
	v_writelane_b32 v254, s40, 61
	v_writelane_b32 v254, s41, 62
	v_readlane_b32 s40, v254, 63
	v_readlane_b32 s41, v255, 0
	s_sub_u32 s40, s40, s43
	s_subb_u32 s41, s41, 0
	s_nop 1
	v_writelane_b32 v254, s40, 63
	v_writelane_b32 v255, s41, 0
	v_readlane_b32 s40, v255, 1
	v_readlane_b32 s41, v255, 2
	s_sub_u32 s40, s40, s43
	s_subb_u32 s41, s41, 0
	s_nop 1
	v_writelane_b32 v255, s40, 1
	v_writelane_b32 v255, s41, 2
	v_readlane_b32 s40, v255, 3
	v_readlane_b32 s41, v255, 4
	s_sub_u32 s40, s40, s43
	s_subb_u32 s41, s41, 0
	s_nop 1
	v_writelane_b32 v255, s40, 3
	v_writelane_b32 v255, s41, 4
.Ltile_fix_done:
	s_mul_i32 s1, s50, 0x780000
	s_mul_hi_i32 s0, s50, 0x780000
	s_add_u32 s24, s12, s1
	s_addc_u32 s25, s13, s0
	s_lshl_b32 s52, s50, 6
	s_ashr_i32 s53, s52, 31
	v_lshlrev_b32_e32 v2, 4, v0
	v_readlane_b32 s0, v254, 60
	v_ashrrev_i32_e32 v34, 3, v0
	v_and_b32_e32 v2, 0x70, v2
	s_add_u32 s0, s24, s0
	v_lshl_or_b32 v196, v34, 11, v2
	s_addc_u32 s1, s25, 0
	v_mov_b32_e32 v197, v1
	v_readlane_b32 s26, v254, 61
	v_readlane_b32 s27, v254, 62
	v_lshl_add_u64 v[30:31], s[0:1], 0, v[196:197]
	v_readlane_b32 s42, v255, 1
	global_load_dwordx4 v[18:21], v196, s[0:1]
	v_add_co_u32_e32 v22, vcc, s33, v30
	s_nop 0
	global_load_dwordx4 v[6:9], v196, s[26:27]
	v_readlane_b32 s26, v254, 63
	v_readlane_b32 s43, v255, 2
	v_readlane_b32 s27, v255, 0
	v_addc_co_u32_e32 v23, vcc, 0, v31, vcc
	v_add_co_u32_e32 v26, vcc, s35, v30
	s_nop 1
	global_load_dwordx4 v[2:5], v196, s[42:43]
	global_load_dwordx4 v[10:13], v196, s[26:27]
	v_readlane_b32 s26, v255, 3
	v_readlane_b32 s27, v255, 4
	v_addc_co_u32_e32 v27, vcc, 0, v31, vcc
	v_add_co_u32_e32 v30, vcc, s39, v30
	v_lshrrev_b32_e32 v35, 4, v0
	s_nop 1
	global_load_dwordx4 v[14:17], v196, s[26:27]
	s_nop 0
	global_load_dwordx4 v[22:25], v[22:23], off
	s_nop 0
	global_load_dwordx4 v[26:29], v[26:27], off
	v_addc_co_u32_e32 v31, vcc, 0, v31, vcc
	global_load_dwordx4 v[30:33], v[30:31], off
	v_bfe_u32 v36, v0, 4, 2
	v_and_b32_e32 v37, 7, v0
	v_lshlrev_b32_e32 v38, 7, v0
	v_lshlrev_b32_e32 v39, 6, v0
	v_xor_b32_e32 v0, v34, v0
	v_bitop3_b32 v35, v35, v37, 3 bitop3:0x6c
	v_bitop3_b32 v36, v36, v37, 4 bitop3:0x36
	v_lshlrev_b32_e32 v0, 4, v0
	s_load_dword s2, s[76:77], 0x0
	v_and_b32_e32 v37, 0x6000, v38
	v_and_b32_e32 v39, 0xffffc000, v39
	v_lshlrev_b32_e32 v35, 4, v35
	v_lshlrev_b32_e32 v36, 4, v36
	v_and_b32_e32 v0, 0x70, v0
	v_readlane_b32 s40, v255, 23
	v_and_b32_e32 v38, 0x780, v38
	v_add_u32_e32 v40, 32, v35
	v_add_u32_e32 v41, 32, v36
	v_add3_u32 v42, s40, v35, v37
	v_add3_u32 v35, s78, v35, v39
	v_lshl_or_b32 v0, v34, 7, v0
	v_add3_u32 v43, s40, v36, v37
	v_add3_u32 v36, s78, v36, v39
	v_add_u32_e32 v34, v40, v37
	v_add_u32_e32 v40, v40, v39
	v_add_u32_e32 v37, v41, v37
	v_add_u32_e32 v39, v41, v39
	v_add_u32_e32 v198, v42, v38
	v_add_u32_e32 v199, v35, v38
	v_add_u32_e32 v35, 0x2000, v0
	v_add_u32_e32 v41, 0x4000, v0
	v_add_u32_e32 v42, 0x6000, v0
	v_add_u32_e32 v203, s40, v0
	v_add_u32_e32 v230, s40, v35
	v_add_u32_e32 v231, s40, v41
	v_add_u32_e32 v232, s40, v42
	v_readlane_b32 s40, v254, 58
	v_readlane_b32 s41, v254, 59
	s_mov_b32 s26, 0
	v_add_u32_e32 v200, v43, v38
	v_add_u32_e32 v201, 32, v0
	s_waitcnt lgkmcnt(0)
	s_lshr_b32 s27, s2, 3
	v_add_u32_e32 v202, s78, v0
	v_add_u32_e32 v204, v34, v38
	v_add_u32_e32 v205, v40, v38
	v_add_u32_e32 v206, v37, v38
	v_add_u32_e32 v207, v39, v38
	v_add_u32_e32 v227, s78, v35
	v_add_u32_e32 v228, s78, v41
	v_add_u32_e32 v229, s78, v42
	v_add_u32_e32 v233, v36, v38
	v_readlane_b32 s46, v254, 13
	s_mov_b32 s66, s40
	s_mov_b64 s[40:41], s[42:43]
	s_waitcnt vmcnt(5)
	ds_write_b128 v201, v[2:5]
	ds_write_b128 v201, v[6:9] offset:8192
	s_waitcnt vmcnt(4)
	ds_write_b128 v201, v[10:13] offset:16384
	s_waitcnt vmcnt(3)
	ds_write_b128 v201, v[14:17] offset:24576
	ds_write_b128 v201, v[18:21] offset:32768
	s_waitcnt vmcnt(2)
	ds_write_b128 v201, v[22:25] offset:40960
	s_waitcnt vmcnt(1)
	ds_write_b128 v201, v[26:29] offset:49152
	s_waitcnt vmcnt(0)
	ds_write_b128 v201, v[30:33] offset:57344
	s_branch .LBB0_79
.Ltile_l1:
	v_readlane_b32 s44, v254, 11
	s_cmpk_lt_u32 s2, 0xb4
	s_cbranch_scc0 .Ltile_l1_b
	s_and_b32 s42, s2, 0xffff
	s_mulk_i32 s42, 0x2d83
	s_lshr_b32 s42, s42, 20
	s_mul_i32 s43, s42, 0x5a
	s_sub_i32 s2, s2, s43
	s_mul_i32 s43, s2, 0xab
	s_bfe_u32 s43, s43, 0x6000a
	s_mul_i32 s45, s43, 6
	s_sub_i32 s2, s2, s45
	s_mul_i32 s42, s42, 6
	s_lshl_b32 s44, s44, 4
	s_add_i32 s42, s42, s44
	s_add_i32 s42, s42, s2
	s_lshl_b32 s56, s42, 8
	s_lshl_b32 s51, s43, 8
	s_branch .LBB0_81
.Ltile_l1_b:
	s_cmpk_lt_u32 s2, 0xf0
	s_cbranch_scc0 .Ltile_l1_c
	s_sub_i32 s2, s2, 0xb4
	s_lshr_b32 s43, s2, 2
	s_and_b32 s2, s2, 3
	s_lshl_b32 s44, s44, 4
	s_add_i32 s42, s44, 12
	s_add_i32 s42, s42, s2
	s_lshl_b32 s56, s42, 8
	s_lshl_b32 s51, s43, 8
	s_branch .LBB0_81
.Ltile_l1_c:
	s_sub_i32 s2, s2, 0xf0
	s_cmp_ge_u32 s2, 7
	s_cselect_b32 s42, 1, 0
	s_cselect_b32 s43, 7, 0
	s_sub_i32 s2, s2, s43
	s_lshl_b32 s2, s2, 2
	s_mov_b32 s43, 0xa875321
	s_lshr_b32 s43, s43, s2
	s_and_b32 s43, s43, 15
	s_lshl_b32 s44, s44, 1
	s_add_i32 s42, s42, s44
	s_addk_i32 s42, 0x80
	s_lshl_b32 s56, s42, 8
	s_lshl_b32 s51, s43, 8
	s_branch .LBB0_81

; template <int EPI>
; DI bool tile_coords(int j, int mpx, int& m0, int& n0) {
;   const int x = blockIdx.x & 7, s = blockIdx.x >> 3, ns = gridDim.x >> 3;
;   const int q = s + ns * j;
;   if constexpr (EPI == 0) {
;     if (q >= mpx * 15) return false;
;     const int panel = q / 90, i = q % 90;
;     const int nt = i / 6, mi = i % 6;
;     m0 = (x * mpx + panel * 6 + mi) * 256;
;     n0 = nt * 256;
; template <int EPI>
; DI void gemm_phase(const P& p, int l, const u16* __restrict__ A, const u16* __restrict__ Bt, int mpx, char* lds) {
;     ...
;   const int tn = t + 1;
;   int m1 = 0, n1 = 0;
;   const bool has_next = tile_coords<EPI>(tn, mpx, m1, n1);
.LBB0_79:
	s_add_i32 s26, s26, 1
	s_mul_i32 s2, s26, s27
	s_add_i32 s2, s2, s84
	s_movk_i32 s42, 0x10d
	s_cmp_eq_u32 s50, 1
	s_cselect_b32 s42, 0xfd, s42
	s_cmp_gt_u32 s2, s42
	s_cselect_b64 s[54:55], -1, 0
	s_and_b64 vcc, exec, s[54:55]
	s_mov_b32 s51, 0
	s_mov_b32 s56, 0
	s_cbranch_vccnz .LBB0_81
	s_cmp_eq_u32 s50, 1
	s_cbranch_scc1 .Ltile_l1
	s_and_b32 s42, s2, 0xffff
	s_mulk_i32 s42, 0x2d83
	s_lshr_b32 s42, s42, 20
	s_mul_i32 s43, s42, 0x5a
	s_sub_i32 s2, s2, s43
	s_mul_i32 s43, s2, 0xab
	s_bfe_u32 s43, s43, 0x6000a
	s_mul_i32 s44, s43, 6
	s_sub_i32 s2, s2, s44
	s_mul_i32 s42, s42, 6
	v_readlane_b32 s44, v254, 12
	s_and_b32 s2, s2, 0xff
	s_add_i32 s42, s44, s42
	s_add_i32 s42, s42, s2
	s_lshl_b32 s56, s42, 8
	s_lshl_b32 s51, s43, 8
